# speedup vs baseline: 1.0044x; 1.0044x over previous
; __device__ __forceinline__ unsigned xb_ld(unsigned* p)              { return __hip_atomic_load(p, __ATOMIC_RELAXED, __HIP_MEMORY_SCOPE_AGENT); }
; __device__ __forceinline__ unsigned xb_add(unsigned* p, unsigned v) { return __hip_atomic_fetch_add(p, v, __ATOMIC_RELAXED, __HIP_MEMORY_SCOPE_AGENT); }
; #define XB_SPIN(cond, bar) do { unsigned _sp = 0; while (cond) { __builtin_amdgcn_s_sleep(1); \
;     if ((++_sp & 255u) == 0u) { if (xb_ld(&(bar)[XB_TMO])) break; if (_sp > XB_SPIN_CAP) { atomicAdd(&(bar)[XB_TMO], 1u); break; } } } } while (0)
; __device__ __forceinline__ void xcd_barrier(const XcdBarrier& b, const bool leader) {
;     ...
;         if (old + 1u == (gen + 1u) * nloc) {
;             __builtin_amdgcn_fence(__ATOMIC_RELEASE, "agent");
;             asm volatile("s_waitcnt vmcnt(0)" ::: "memory");
;             const unsigned og = xb_add(&bar[XB_TOP], 1u);
;             const unsigned tg = og / nx;
;             if (og + 1u == (tg + 1u) * nx) xb_add(&bar[XB_TOPGEN], 1u);
;             else XB_SPIN(xb_ld(&bar[XB_TOPGEN]) == tg, bar);
;             __builtin_amdgcn_fence(__ATOMIC_ACQUIRE, "agent");
;             xb_add(&bar[XB_XGEN(b.x)], 1u);
;             asm volatile("s_waitcnt vmcnt(0)" ::: "memory");
.LBB0_392:
	s_or_b64 exec, exec, s[14:15]
	s_mov_b64 s[14:15], exec
	v_mbcnt_lo_u32_b32 v0, s14, 0
	v_mbcnt_hi_u32_b32 v0, s15, v0
	v_cmp_eq_u32_e32 vcc, 0, v0
	s_waitcnt vmcnt(0)
	buffer_inv sc1
	s_and_saveexec_b64 s[38:39], vcc
	s_cbranch_execz .LBB0_394
	s_bcnt1_i32_b64 s6, s[14:15]
	v_mov_b32_e32 v0, s6
	v_readlane_b32 s6, v255, 51
	v_readlane_b32 s7, v255, 52
	s_nop 4
.LBB0_394:
	s_or_b64 exec, exec, s[38:39]
	s_waitcnt vmcnt(0)

; __device__ __forceinline__ unsigned xb_ld(unsigned* p)              { return __hip_atomic_load(p, __ATOMIC_RELAXED, __HIP_MEMORY_SCOPE_AGENT); }
; __device__ __forceinline__ unsigned xb_add(unsigned* p, unsigned v) { return __hip_atomic_fetch_add(p, v, __ATOMIC_RELAXED, __HIP_MEMORY_SCOPE_AGENT); }
; #define XB_SPIN(cond, bar) do { unsigned _sp = 0; while (cond) { __builtin_amdgcn_s_sleep(1); \
;     if ((++_sp & 255u) == 0u) { if (xb_ld(&(bar)[XB_TMO])) break; if (_sp > XB_SPIN_CAP) { atomicAdd(&(bar)[XB_TMO], 1u); break; } } } } while (0)
; __device__ __forceinline__ void xcd_barrier(const XcdBarrier& b, const bool leader) {
;     ...
;         if (old + 1u == (gen + 1u) * nloc) {
;             __builtin_amdgcn_fence(__ATOMIC_RELEASE, "agent");
;             asm volatile("s_waitcnt vmcnt(0)" ::: "memory");
;             const unsigned og = xb_add(&bar[XB_TOP], 1u);
;             const unsigned tg = og / nx;
;             if (og + 1u == (tg + 1u) * nx) xb_add(&bar[XB_TOPGEN], 1u);
;             else XB_SPIN(xb_ld(&bar[XB_TOPGEN]) == tg, bar);
;             __builtin_amdgcn_fence(__ATOMIC_ACQUIRE, "agent");
;             xb_add(&bar[XB_XGEN(b.x)], 1u);
;             asm volatile("s_waitcnt vmcnt(0)" ::: "memory");
.LBB0_506:
	s_or_b64 exec, exec, s[14:15]
	s_mov_b64 s[14:15], exec
	v_mbcnt_lo_u32_b32 v0, s14, 0
	v_mbcnt_hi_u32_b32 v0, s15, v0
	v_cmp_eq_u32_e32 vcc, 0, v0
	s_waitcnt vmcnt(0)
	buffer_inv sc1
	s_and_saveexec_b64 s[40:41], vcc
	s_cbranch_execz .LBB0_508
	s_bcnt1_i32_b64 s6, s[14:15]
	v_mov_b32_e32 v0, s6
	v_readlane_b32 s6, v255, 51
	v_readlane_b32 s7, v255, 52
	s_nop 4
.LBB0_508:
	s_or_b64 exec, exec, s[40:41]
	s_waitcnt vmcnt(0)

; __device__ __forceinline__ unsigned xb_ld(unsigned* p)              { return __hip_atomic_load(p, __ATOMIC_RELAXED, __HIP_MEMORY_SCOPE_AGENT); }
; __device__ __forceinline__ unsigned xb_add(unsigned* p, unsigned v) { return __hip_atomic_fetch_add(p, v, __ATOMIC_RELAXED, __HIP_MEMORY_SCOPE_AGENT); }
; #define XB_SPIN(cond, bar) do { unsigned _sp = 0; while (cond) { __builtin_amdgcn_s_sleep(1); \
;     if ((++_sp & 255u) == 0u) { if (xb_ld(&(bar)[XB_TMO])) break; if (_sp > XB_SPIN_CAP) { atomicAdd(&(bar)[XB_TMO], 1u); break; } } } } while (0)
; __device__ __forceinline__ void xcd_barrier(const XcdBarrier& b, const bool leader) {
;     ...
;         if (old + 1u == (gen + 1u) * nloc) {
;             __builtin_amdgcn_fence(__ATOMIC_RELEASE, "agent");
;             asm volatile("s_waitcnt vmcnt(0)" ::: "memory");
;             const unsigned og = xb_add(&bar[XB_TOP], 1u);
;             const unsigned tg = og / nx;
;             if (og + 1u == (tg + 1u) * nx) xb_add(&bar[XB_TOPGEN], 1u);
;             else XB_SPIN(xb_ld(&bar[XB_TOPGEN]) == tg, bar);
;             __builtin_amdgcn_fence(__ATOMIC_ACQUIRE, "agent");
;             xb_add(&bar[XB_XGEN(b.x)], 1u);
;             asm volatile("s_waitcnt vmcnt(0)" ::: "memory");
.LBB0_598:
	s_or_b64 exec, exec, s[14:15]
	s_mov_b64 s[14:15], exec
	v_mbcnt_lo_u32_b32 v0, s14, 0
	v_mbcnt_hi_u32_b32 v0, s15, v0
	v_cmp_eq_u32_e32 vcc, 0, v0
	s_waitcnt vmcnt(0)
	buffer_inv sc1
	s_and_saveexec_b64 s[38:39], vcc
	s_cbranch_execz .LBB0_600
	s_bcnt1_i32_b64 s6, s[14:15]
	v_mov_b32_e32 v0, s6
	v_readlane_b32 s6, v255, 51
	v_readlane_b32 s7, v255, 52
	s_nop 4
.LBB0_600:
	s_or_b64 exec, exec, s[38:39]
	s_waitcnt vmcnt(0)

; __device__ __forceinline__ unsigned xb_ld(unsigned* p)              { return __hip_atomic_load(p, __ATOMIC_RELAXED, __HIP_MEMORY_SCOPE_AGENT); }
; __device__ __forceinline__ unsigned xb_add(unsigned* p, unsigned v) { return __hip_atomic_fetch_add(p, v, __ATOMIC_RELAXED, __HIP_MEMORY_SCOPE_AGENT); }
; #define XB_SPIN(cond, bar) do { unsigned _sp = 0; while (cond) { __builtin_amdgcn_s_sleep(1); \
;     if ((++_sp & 255u) == 0u) { if (xb_ld(&(bar)[XB_TMO])) break; if (_sp > XB_SPIN_CAP) { atomicAdd(&(bar)[XB_TMO], 1u); break; } } } } while (0)
; __device__ __forceinline__ void xcd_barrier(const XcdBarrier& b, const bool leader) {
;     ...
;         if (old + 1u == (gen + 1u) * nloc) {
;             __builtin_amdgcn_fence(__ATOMIC_RELEASE, "agent");
;             asm volatile("s_waitcnt vmcnt(0)" ::: "memory");
;             const unsigned og = xb_add(&bar[XB_TOP], 1u);
;             const unsigned tg = og / nx;
;             if (og + 1u == (tg + 1u) * nx) xb_add(&bar[XB_TOPGEN], 1u);
;             else XB_SPIN(xb_ld(&bar[XB_TOPGEN]) == tg, bar);
;             __builtin_amdgcn_fence(__ATOMIC_ACQUIRE, "agent");
;             xb_add(&bar[XB_XGEN(b.x)], 1u);
;             asm volatile("s_waitcnt vmcnt(0)" ::: "memory");
.LBB0_654:
	s_or_b64 exec, exec, s[14:15]
	s_mov_b64 s[14:15], exec
	v_mbcnt_lo_u32_b32 v0, s14, 0
	v_mbcnt_hi_u32_b32 v0, s15, v0
	v_cmp_eq_u32_e32 vcc, 0, v0
	s_waitcnt vmcnt(0)
	buffer_inv sc1
	s_and_saveexec_b64 s[36:37], vcc
	s_cbranch_execz .LBB0_656
	s_bcnt1_i32_b64 s6, s[14:15]
	v_mov_b32_e32 v0, s6
	v_readlane_b32 s6, v255, 51
	v_readlane_b32 s7, v255, 52
	s_nop 4
.LBB0_656:
	s_or_b64 exec, exec, s[36:37]
	s_waitcnt vmcnt(0)

; __device__ __forceinline__ unsigned xb_ld(unsigned* p)              { return __hip_atomic_load(p, __ATOMIC_RELAXED, __HIP_MEMORY_SCOPE_AGENT); }
; __device__ __forceinline__ unsigned xb_add(unsigned* p, unsigned v) { return __hip_atomic_fetch_add(p, v, __ATOMIC_RELAXED, __HIP_MEMORY_SCOPE_AGENT); }
; #define XB_SPIN(cond, bar) do { unsigned _sp = 0; while (cond) { __builtin_amdgcn_s_sleep(1); \
;     if ((++_sp & 255u) == 0u) { if (xb_ld(&(bar)[XB_TMO])) break; if (_sp > XB_SPIN_CAP) { atomicAdd(&(bar)[XB_TMO], 1u); break; } } } } while (0)
; __device__ __forceinline__ void xcd_barrier(const XcdBarrier& b, const bool leader) {
;     ...
;         if (old + 1u == (gen + 1u) * nloc) {
;             __builtin_amdgcn_fence(__ATOMIC_RELEASE, "agent");
;             asm volatile("s_waitcnt vmcnt(0)" ::: "memory");
;             const unsigned og = xb_add(&bar[XB_TOP], 1u);
;             const unsigned tg = og / nx;
;             if (og + 1u == (tg + 1u) * nx) xb_add(&bar[XB_TOPGEN], 1u);
;             else XB_SPIN(xb_ld(&bar[XB_TOPGEN]) == tg, bar);
;             __builtin_amdgcn_fence(__ATOMIC_ACQUIRE, "agent");
;             xb_add(&bar[XB_XGEN(b.x)], 1u);
;             asm volatile("s_waitcnt vmcnt(0)" ::: "memory");
.LBB0_736:
	s_or_b64 exec, exec, s[14:15]
	s_mov_b64 s[14:15], exec
	v_mbcnt_lo_u32_b32 v0, s14, 0
	v_mbcnt_hi_u32_b32 v0, s15, v0
	v_cmp_eq_u32_e32 vcc, 0, v0
	s_waitcnt vmcnt(0)
	buffer_inv sc1
	s_and_saveexec_b64 s[38:39], vcc
	s_cbranch_execz .LBB0_738
	s_bcnt1_i32_b64 s6, s[14:15]
	v_mov_b32_e32 v0, s6
	v_readlane_b32 s6, v255, 51
	v_readlane_b32 s7, v255, 52
	s_nop 4
.LBB0_738:
	s_or_b64 exec, exec, s[38:39]
	s_waitcnt vmcnt(0)

; __device__ __forceinline__ unsigned xb_ld(unsigned* p)              { return __hip_atomic_load(p, __ATOMIC_RELAXED, __HIP_MEMORY_SCOPE_AGENT); }
; __device__ __forceinline__ unsigned xb_add(unsigned* p, unsigned v) { return __hip_atomic_fetch_add(p, v, __ATOMIC_RELAXED, __HIP_MEMORY_SCOPE_AGENT); }
; #define XB_SPIN(cond, bar) do { unsigned _sp = 0; while (cond) { __builtin_amdgcn_s_sleep(1); \
;     if ((++_sp & 255u) == 0u) { if (xb_ld(&(bar)[XB_TMO])) break; if (_sp > XB_SPIN_CAP) { atomicAdd(&(bar)[XB_TMO], 1u); break; } } } } while (0)
; __device__ __forceinline__ void xcd_barrier(const XcdBarrier& b, const bool leader) {
;     ...
;         if (old + 1u == (gen + 1u) * nloc) {
;             __builtin_amdgcn_fence(__ATOMIC_RELEASE, "agent");
;             asm volatile("s_waitcnt vmcnt(0)" ::: "memory");
;             const unsigned og = xb_add(&bar[XB_TOP], 1u);
;             const unsigned tg = og / nx;
;             if (og + 1u == (tg + 1u) * nx) xb_add(&bar[XB_TOPGEN], 1u);
;             else XB_SPIN(xb_ld(&bar[XB_TOPGEN]) == tg, bar);
;             __builtin_amdgcn_fence(__ATOMIC_ACQUIRE, "agent");
;             xb_add(&bar[XB_XGEN(b.x)], 1u);
;             asm volatile("s_waitcnt vmcnt(0)" ::: "memory");
.LBB0_792:
	s_or_b64 exec, exec, s[14:15]
	s_mov_b64 s[14:15], exec
	v_mbcnt_lo_u32_b32 v0, s14, 0
	v_mbcnt_hi_u32_b32 v0, s15, v0
	v_cmp_eq_u32_e32 vcc, 0, v0
	s_waitcnt vmcnt(0)
	buffer_inv sc1
	s_and_saveexec_b64 s[36:37], vcc
	s_cbranch_execz .LBB0_794
	s_bcnt1_i32_b64 s6, s[14:15]
	v_mov_b32_e32 v0, s6
	v_readlane_b32 s6, v255, 51
	v_readlane_b32 s7, v255, 52
	s_nop 4
.LBB0_794:
	s_or_b64 exec, exec, s[36:37]
	s_waitcnt vmcnt(0)

; __device__ __forceinline__ unsigned xb_ld(unsigned* p)              { return __hip_atomic_load(p, __ATOMIC_RELAXED, __HIP_MEMORY_SCOPE_AGENT); }
; __device__ __forceinline__ unsigned xb_add(unsigned* p, unsigned v) { return __hip_atomic_fetch_add(p, v, __ATOMIC_RELAXED, __HIP_MEMORY_SCOPE_AGENT); }
; #define XB_SPIN(cond, bar) do { unsigned _sp = 0; while (cond) { __builtin_amdgcn_s_sleep(1); \
;     if ((++_sp & 255u) == 0u) { if (xb_ld(&(bar)[XB_TMO])) break; if (_sp > XB_SPIN_CAP) { atomicAdd(&(bar)[XB_TMO], 1u); break; } } } } while (0)
; __device__ __forceinline__ void xcd_barrier(const XcdBarrier& b, const bool leader) {
;     ...
;         if (old + 1u == (gen + 1u) * nloc) {
;             __builtin_amdgcn_fence(__ATOMIC_RELEASE, "agent");
;             asm volatile("s_waitcnt vmcnt(0)" ::: "memory");
;             const unsigned og = xb_add(&bar[XB_TOP], 1u);
;             const unsigned tg = og / nx;
;             if (og + 1u == (tg + 1u) * nx) xb_add(&bar[XB_TOPGEN], 1u);
;             else XB_SPIN(xb_ld(&bar[XB_TOPGEN]) == tg, bar);
;             __builtin_amdgcn_fence(__ATOMIC_ACQUIRE, "agent");
;             xb_add(&bar[XB_XGEN(b.x)], 1u);
;             asm volatile("s_waitcnt vmcnt(0)" ::: "memory");
.LBB0_921:
	s_or_b64 exec, exec, s[14:15]
	s_mov_b64 s[14:15], exec
	v_mbcnt_lo_u32_b32 v0, s14, 0
	v_mbcnt_hi_u32_b32 v0, s15, v0
	v_cmp_eq_u32_e32 vcc, 0, v0
	s_waitcnt vmcnt(0)
	buffer_inv sc1
	s_and_saveexec_b64 s[40:41], vcc
	s_cbranch_execz .LBB0_923
	s_bcnt1_i32_b64 s6, s[14:15]
	v_mov_b32_e32 v0, s6
	v_readlane_b32 s6, v255, 51
	v_readlane_b32 s7, v255, 52
	s_nop 4
.LBB0_923:
	s_or_b64 exec, exec, s[40:41]
	s_waitcnt vmcnt(0)

; __device__ __forceinline__ unsigned xb_ld(unsigned* p)              { return __hip_atomic_load(p, __ATOMIC_RELAXED, __HIP_MEMORY_SCOPE_AGENT); }
; __device__ __forceinline__ unsigned xb_add(unsigned* p, unsigned v) { return __hip_atomic_fetch_add(p, v, __ATOMIC_RELAXED, __HIP_MEMORY_SCOPE_AGENT); }
; #define XB_SPIN(cond, bar) do { unsigned _sp = 0; while (cond) { __builtin_amdgcn_s_sleep(1); \
;     if ((++_sp & 255u) == 0u) { if (xb_ld(&(bar)[XB_TMO])) break; if (_sp > XB_SPIN_CAP) { atomicAdd(&(bar)[XB_TMO], 1u); break; } } } } while (0)
; __device__ __forceinline__ void xcd_barrier(const XcdBarrier& b, const bool leader) {
;     ...
;         if (old + 1u == (gen + 1u) * nloc) {
;             __builtin_amdgcn_fence(__ATOMIC_RELEASE, "agent");
;             asm volatile("s_waitcnt vmcnt(0)" ::: "memory");
;             const unsigned og = xb_add(&bar[XB_TOP], 1u);
;             const unsigned tg = og / nx;
;             if (og + 1u == (tg + 1u) * nx) xb_add(&bar[XB_TOPGEN], 1u);
;             else XB_SPIN(xb_ld(&bar[XB_TOPGEN]) == tg, bar);
;             __builtin_amdgcn_fence(__ATOMIC_ACQUIRE, "agent");
;             xb_add(&bar[XB_XGEN(b.x)], 1u);
;             asm volatile("s_waitcnt vmcnt(0)" ::: "memory");
.LBB0_983:
	s_or_b64 exec, exec, s[14:15]
	s_mov_b64 s[14:15], exec
	v_mbcnt_lo_u32_b32 v0, s14, 0
	v_mbcnt_hi_u32_b32 v0, s15, v0
	v_cmp_eq_u32_e32 vcc, 0, v0
	s_waitcnt vmcnt(0)
	buffer_inv sc1
	s_and_saveexec_b64 s[36:37], vcc
	s_cbranch_execz .LBB0_985
	s_bcnt1_i32_b64 s6, s[14:15]
	v_mov_b32_e32 v0, s6
	v_readlane_b32 s6, v255, 51
	v_readlane_b32 s7, v255, 52
	s_nop 4
.LBB0_985:
	s_or_b64 exec, exec, s[36:37]
	s_waitcnt vmcnt(0)

; __device__ __forceinline__ unsigned xb_ld(unsigned* p)              { return __hip_atomic_load(p, __ATOMIC_RELAXED, __HIP_MEMORY_SCOPE_AGENT); }
; __device__ __forceinline__ unsigned xb_add(unsigned* p, unsigned v) { return __hip_atomic_fetch_add(p, v, __ATOMIC_RELAXED, __HIP_MEMORY_SCOPE_AGENT); }
; #define XB_SPIN(cond, bar) do { unsigned _sp = 0; while (cond) { __builtin_amdgcn_s_sleep(1); \
;     if ((++_sp & 255u) == 0u) { if (xb_ld(&(bar)[XB_TMO])) break; if (_sp > XB_SPIN_CAP) { atomicAdd(&(bar)[XB_TMO], 1u); break; } } } } while (0)
; __device__ __forceinline__ void xcd_barrier(const XcdBarrier& b, const bool leader) {
;     ...
;         if (old + 1u == (gen + 1u) * nloc) {
;             __builtin_amdgcn_fence(__ATOMIC_RELEASE, "agent");
;             asm volatile("s_waitcnt vmcnt(0)" ::: "memory");
;             const unsigned og = xb_add(&bar[XB_TOP], 1u);
;             const unsigned tg = og / nx;
;             if (og + 1u == (tg + 1u) * nx) xb_add(&bar[XB_TOPGEN], 1u);
;             else XB_SPIN(xb_ld(&bar[XB_TOPGEN]) == tg, bar);
;             __builtin_amdgcn_fence(__ATOMIC_ACQUIRE, "agent");
;             xb_add(&bar[XB_XGEN(b.x)], 1u);
;             asm volatile("s_waitcnt vmcnt(0)" ::: "memory");
.LBB0_1129:
	s_bcnt1_i32_b64 s6, s[14:15]
	v_mov_b32_e32 v0, s6
	v_readlane_b32 s6, v255, 51
	v_readlane_b32 s7, v255, 52
	s_nop 4
	s_getpc_b64 s[98:99]
